# RESID epilogue: x prefetch loads issued at epilogue entry (before the accumulator staging) on top of the regenerated row chunks
# speedup vs baseline: 1.0110x; 1.0110x over previous
; DI float fexp2(float x) { return __builtin_amdgcn_exp2f(x); }
; template <int EPI>
; DI void gemm_epilogue(const Ep& e, int m0, int n0) {
;     ...
;       const int row = p * 32 + (t >> 4), c8 = (t & 15) * 8;
;       const float4 a = *(const float4*)(T + row * 132 + c8), b = *(const float4*)(T + row * 132 + c8 + 4);
;       bf16_t* bp = e.xb + (size_t)(m0 + row) * DM + n0 + c8;
;       const uint4 xo4 = *(const uint4*)bp;
;     ...
;   if (t < 256) {
;     float rs = 1.f;
;     if (e.ss) {
;       const float* sp = e.ss + (size_t)(m0 + t) * e.nss;
;       float s = 0.f;
;       for (int i = 0; i < e.nss; ++i) s += sp[i];
;       rs = rsqrtf(s * e.inv_n + EPS);
;     }
;     ((float*)(smem + SMEM_RSTD))[t] = rs;
;   }
;   if constexpr (EPI == EPI_GU) {
;     __syncthreads();
;     const float* rstdL = (const float*)(smem + SMEM_RSTD);
; #pragma unroll
;     for (int ai = 0; ai < 2; ++ai)
; #pragma unroll
;       for (int m = 0; m < 4; ++m) {
;         const int rowb = ai * 128 + wr * 64 + m * 16 + fq * 4;
;         const f32x4 rs4 = *(const f32x4*)(rstdL + rowb);
; #pragma unroll
;         for (int bj = 0; bj < 2; ++bj) {
;           bf16_t* op = e.out + (size_t)(m0 + rowb) * e.ldo + ((n0 + bj * 128 + wc * 32) >> 1) + fr;
; #pragma unroll
;           for (int j = 0; j < 4; ++j) {
;             const float g = acc[ai][bj][m][0][j] * rs4[j], u = acc[ai][bj][m][1][j] * rs4[j];
;             const float rv = g * __builtin_amdgcn_rcpf(1.f + fexp2(-g * LOG2E)) * u;
;             op[(size_t)j * e.ldo] = (bf16_t)(pack2(rv, 0.f) & 0xffffu);
;           }
;         }
;       }
;     __syncthreads();
;     return;
;   }
;   float* T = (float*)smem;
; #pragma unroll
;   for (int bj = 0; bj < 2; ++bj) {
; #pragma unroll
;     for (int ai = 0; ai < 2; ++ai)
; #pragma unroll
;       for (int m = 0; m < 4; ++m)
; #pragma unroll
;         for (int n = 0; n < 2; ++n)
; #pragma unroll
;           for (int j = 0; j < 4; ++j)
;             T[(ai * 128 + wr * 64 + m * 16 + fq * 4 + j) * 132 + wc * 32 + n * 16 + fr] = acc[ai][bj][m][n][j];
;     __syncthreads();
.LBB0_911:
	s_or_b64 exec, exec, s[2:3]
	s_movk_i32 s2, 0x100
	v_cmp_gt_i32_e32 vcc, s2, v3
	s_waitcnt vmcnt(0)
	v_lshrrev_b32_e32 v220, 4, v224
	v_add_u32_e32 v220, s25, v220
	v_mov_b32_e32 v221, 0
	v_lshlrev_b64 v[220:221], 11, v[220:221]
	v_lshl_add_u64 v[220:221], s[6:7], 0, v[220:221]
	v_lshl_add_u64 v[220:221], s[8:9], 1, v[220:221]
	v_and_b32_e32 v222, 15, v224
	v_lshlrev_b32_e32 v222, 4, v222
	v_mov_b32_e32 v223, 0
	v_lshl_add_u64 v[250:251], v[220:221], 0, v[222:223]
	v_mov_b32_e32 v226, 0x10000
	v_mov_b32_e32 v227, 0
	global_load_dwordx4 v[156:159], v[250:251], off
	v_lshl_add_u64 v[236:237], v[250:251], 0, v[226:227]
	global_load_dwordx4 v[160:163], v[236:237], off
	v_lshl_add_u64 v[238:239], v[236:237], 0, v[226:227]
	global_load_dwordx4 v[164:167], v[238:239], off
	v_lshl_add_u64 v[240:241], v[238:239], 0, v[226:227]
	global_load_dwordx4 v[168:171], v[240:241], off
	v_lshl_add_u64 v[242:243], v[240:241], 0, v[226:227]
	global_load_dwordx4 v[172:175], v[242:243], off
	v_lshl_add_u64 v[244:245], v[242:243], 0, v[226:227]
	global_load_dwordx4 v[176:179], v[244:245], off
	v_lshl_add_u64 v[246:247], v[244:245], 0, v[226:227]
	global_load_dwordx4 v[180:183], v[246:247], off
	v_lshl_add_u64 v[248:249], v[246:247], 0, v[226:227]
	global_load_dwordx4 v[184:187], v[248:249], off
	global_load_dwordx4 v[188:191], v[250:251], off offset:256
	global_load_dwordx4 v[192:195], v[236:237], off offset:256
	global_load_dwordx4 v[196:199], v[238:239], off offset:256
	global_load_dwordx4 v[200:203], v[240:241], off offset:256
	global_load_dwordx4 v[204:207], v[242:243], off offset:256
	global_load_dwordx4 v[208:211], v[244:245], off offset:256
	global_load_dwordx4 v[212:215], v[246:247], off offset:256
	global_load_dwordx4 v[216:219], v[248:249], off offset:256
	s_barrier
	s_and_saveexec_b64 s[2:3], vcc
	v_lshl_add_u32 v0, v3, 2, v234
	v_mov_b32_e32 v1, 1.0
	ds_write_b32 v0, v1
	s_or_b64 exec, exec, s[2:3]
	v_lshl_or_b32 v0, v148, 2, v149
	v_lshlrev_b32_e32 v1, 2, v147
	s_movk_i32 s12, 0x210
	v_lshl_or_b32 v1, v146, 7, v1
	v_mul_lo_u32 v0, v0, s12
	v_add_u32_e32 v132, v1, v0
	ds_write2_b32 v132, v104, v116 offset1:16
	ds_write2_b32 v132, v105, v117 offset0:132 offset1:148
	v_add_u32_e32 v104, 0x400, v132
	v_add_u32_e32 v105, 0x2000, v132
	ds_write2_b32 v104, v106, v118 offset0:8 offset1:24
	ds_write2_b32 v104, v107, v119 offset0:140 offset1:156
	ds_write2_b32 v105, v100, v108 offset0:64 offset1:80
	ds_write2_b32 v105, v101, v109 offset0:196 offset1:212
	v_add_u32_e32 v100, 0x2400, v132
	v_add_u32_e32 v101, 0x4000, v132
	ds_write2_b32 v100, v102, v110 offset0:72 offset1:88
	ds_write2_b32 v100, v103, v111 offset0:204 offset1:220
	ds_write2_b32 v101, v92, v96 offset0:128 offset1:144
	v_add_u32_e32 v92, 0x4400, v132
	ds_write2_b32 v92, v93, v97 offset0:4 offset1:20
	ds_write2_b32 v92, v94, v98 offset0:136 offset1:152
	v_add_u32_e32 v94, 0x6000, v132
	v_add_u32_e32 v93, 0x4800, v132
	ds_write2_b32 v94, v84, v88 offset0:192 offset1:208
	v_add_u32_e32 v84, 0x6400, v132
	v_or_b32_e32 v3, 64, v1
	ds_write2_b32 v93, v95, v99 offset0:12 offset1:28
	ds_write2_b32 v84, v85, v89 offset0:68 offset1:84
	ds_write2_b32 v84, v86, v90 offset0:200 offset1:216
	v_add_u32_e32 v85, 0x6800, v132
	v_add_u32_e32 v90, 0x10800, v0
	ds_write2_b32 v85, v87, v91 offset0:76 offset1:92
	v_add_u32_e32 v86, v1, v90
	v_add_u32_e32 v91, 0x10a10, v0
	v_add_u32_e32 v90, v3, v90
	v_add_u32_e32 v95, 0x10c20, v0
	ds_write_b32 v90, v124
	v_add_u32_e32 v90, v3, v91
	v_add_u32_e32 v96, 0x10e30, v0
	ds_write_b32 v90, v125
	v_add_u32_e32 v90, v3, v95
	ds_write_b32 v90, v126
	v_add_u32_e32 v90, v3, v96
	v_add_u32_e32 v97, 0x12900, v0
	ds_write_b32 v90, v127
	v_add_u32_e32 v90, v1, v97
	v_add_u32_e32 v98, 0x12b10, v0
	v_add_u32_e32 v97, v3, v97
	v_add_u32_e32 v99, 0x12d20, v0
	ds_write_b32 v97, v112
	v_add_u32_e32 v97, v3, v98
	v_add_u32_e32 v102, 0x12f30, v0
	ds_write_b32 v97, v113
	v_add_u32_e32 v97, v3, v99
	v_add_u32_e32 v87, v1, v91
	v_add_u32_e32 v91, v1, v98
	ds_write_b32 v97, v114
	v_add_u32_e32 v97, v3, v102
	v_add_u32_e32 v98, 0x14a00, v0
	v_add_u32_e32 v88, v1, v95
	v_add_u32_e32 v95, v1, v99
	ds_write_b32 v97, v115
	v_add_u32_e32 v97, v1, v98
	v_add_u32_e32 v99, 0x14c10, v0
	v_add_u32_e32 v89, v1, v96
	v_add_u32_e32 v96, v1, v102
	ds_write_b32 v97, v80
	v_add_u32_e32 v80, v1, v99
	v_add_u32_e32 v102, 0x14e20, v0
	ds_write_b32 v80, v81
	v_add_u32_e32 v81, v1, v102
	v_add_u32_e32 v103, 0x15030, v0
	ds_write_b32 v81, v82
	v_add_u32_e32 v82, v1, v103
	ds_write_b32 v82, v83
	v_add_u32_e32 v83, v3, v98
	ds_write_b32 v83, v76
	v_add_u32_e32 v76, v3, v99
	ds_write_b32 v76, v77
	v_add_u32_e32 v76, v3, v102
	ds_write_b32 v76, v78
	v_add_u32_e32 v76, v3, v103
	v_add_u32_e32 v83, 0x16b00, v0
	ds_write_b32 v76, v79
	v_add_u32_e32 v76, v1, v83
	ds_write_b32 v76, v72
	v_add_u32_e32 v72, 0x16d10, v0
	v_add_u32_e32 v77, v1, v72
	ds_write_b32 v77, v73
	v_add_u32_e32 v73, 0x16f20, v0
	v_add_u32_e32 v0, 0x17130, v0
	v_add_u32_e32 v78, v1, v73
	v_add_u32_e32 v79, v1, v0
	v_add_u32_e32 v1, v3, v83
	ds_write_b32 v1, v68
	v_add_u32_e32 v1, v3, v72
	ds_write_b32 v1, v69
	v_add_u32_e32 v1, v3, v73
	v_add_u32_e32 v0, v3, v0
	v_mov_b32_e32 v73, v224
	ds_write_b32 v86, v128
	ds_write_b32 v87, v129
	ds_write_b32 v88, v130
	ds_write_b32 v89, v131
	ds_write_b32 v90, v120
	ds_write_b32 v91, v121
	ds_write_b32 v95, v122
	ds_write_b32 v96, v123
	ds_write_b32 v78, v74
	ds_write_b32 v79, v75
	ds_write_b32 v1, v70
	ds_write_b32 v0, v71
	s_waitcnt lgkmcnt(0)
	s_barrier
; DI float h_lo(unsigned u) { return (float)__builtin_bit_cast(h2_t, u)[0]; }
; DI float h_hi(unsigned u) { return (float)__builtin_bit_cast(h2_t, u)[1]; }
; template <int EPI>
; DI void gemm_epilogue(const Ep& e, int m0, int n0) {
;     ...
;   } else if constexpr (EPI == EPI_RESID) {
; #pragma unroll
;     for (int p = 0; p < 8; ++p) {
;       const int row = p * 32 + (t >> 4), c8 = (t & 15) * 8;
;       const float4 a = *(const float4*)(T + row * 132 + c8), b = *(const float4*)(T + row * 132 + c8 + 4);
;       bf16_t* bp = e.xb + (size_t)(m0 + row) * DM + n0 + c8;
;       const uint4 xo4 = *(const uint4*)bp;
;       uint4 u;
;       u.x = pack2h(h_lo(xo4.x) + a.x, h_hi(xo4.x) + a.y); u.y = pack2h(h_lo(xo4.y) + a.z, h_hi(xo4.y) + a.w);
;       u.z = pack2h(h_lo(xo4.z) + b.x, h_hi(xo4.z) + b.y); u.w = pack2h(h_lo(xo4.w) + b.z, h_hi(xo4.w) + b.w);
;       *(uint4*)bp = u;
;       const float r0 = h_lo(u.x), r1 = h_hi(u.x), r2 = h_lo(u.y), r3 = h_hi(u.y);
;       const float r4 = h_lo(u.z), r5 = h_hi(u.z), r6 = h_lo(u.w), r7 = h_hi(u.w);
;       float s2 = r0 * r0 + r1 * r1 + r2 * r2 + r3 * r3 + r4 * r4 + r5 * r5 + r6 * r6 + r7 * r7;
;       s2 += __shfl_xor(s2, 1); s2 += __shfl_xor(s2, 2); s2 += __shfl_xor(s2, 4);
;       if ((t & 7) == 0) e.ss_out[(size_t)(m0 + row) * 16 + ((n0 + c8) >> 6)] = s2;
;     }
;     return;
	s_add_u32 s2, s0, 0xf640000
	s_addc_u32 s3, s1, 0
	v_lshrrev_b32_e32 v220, 4, v224
	v_and_b32_e32 v221, 15, v224
	v_mul_u32_u24_e32 v98, 0x210, v220
	v_lshl_add_u32 v98, v221, 5, v98
	v_add_u32_e32 v99, 0x10800, v98
	v_and_b32_e32 v233, 7, v224
	v_cmp_eq_u32_e64 s[100:101], 0, v233
	v_lshlrev_b32_e32 v221, 3, v221
	v_or_b32_e32 v221, s8, v221
	v_ashrrev_i32_e32 v221, 6, v221
	v_add_u32_e32 v220, s25, v220
	v_lshlrev_b32_e32 v220, 6, v220
	v_lshl_add_u32 v222, v221, 2, v220
	ds_read_b128 v[106:109], v98
	ds_read_b128 v[110:113], v98 offset:16
	ds_read_b128 v[68:71], v98 offset:16896
	ds_read_b128 v[72:75], v98 offset:16912
	s_waitcnt vmcnt(15)
	s_waitcnt lgkmcnt(2)
	v_fma_mix_f32 v106, v156, 1.0, v106 op_sel_hi:[1,0,0]
	v_fma_mix_f32 v107, v156, 1.0, v107 op_sel:[1,0,0] op_sel_hi:[1,0,0]
	v_fma_mix_f32 v108, v157, 1.0, v108 op_sel_hi:[1,0,0]
	v_fma_mix_f32 v109, v157, 1.0, v109 op_sel:[1,0,0] op_sel_hi:[1,0,0]
	v_fma_mix_f32 v110, v158, 1.0, v110 op_sel_hi:[1,0,0]
	v_fma_mix_f32 v111, v158, 1.0, v111 op_sel:[1,0,0] op_sel_hi:[1,0,0]
	v_fma_mix_f32 v112, v159, 1.0, v112 op_sel_hi:[1,0,0]
	v_fma_mix_f32 v113, v159, 1.0, v113 op_sel:[1,0,0] op_sel_hi:[1,0,0]
	v_cvt_pk_f16_f32 v114, v106, v107
	v_cvt_pk_f16_f32 v115, v108, v109
	v_cvt_pk_f16_f32 v116, v110, v111
	v_cvt_pk_f16_f32 v117, v112, v113
	global_store_dwordx4 v[250:251], v[114:117], off
	ds_read_b128 v[106:109], v98 offset:33792
	ds_read_b128 v[110:113], v98 offset:33808
	s_waitcnt vmcnt(15)
	s_waitcnt lgkmcnt(2)
	v_fma_mix_f32 v68, v160, 1.0, v68 op_sel_hi:[1,0,0]
	v_fma_mix_f32 v118, v114, v114, 0 op_sel:[1,1,0] op_sel_hi:[1,1,0]
	v_fma_mix_f32 v69, v160, 1.0, v69 op_sel:[1,0,0] op_sel_hi:[1,0,0]
	v_fma_mix_f32 v118, v114, v114, v118 op_sel_hi:[1,1,0]
	v_fma_mix_f32 v70, v161, 1.0, v70 op_sel_hi:[1,0,0]
	v_fma_mix_f32 v118, v115, v115, v118 op_sel_hi:[1,1,0]
	v_fma_mix_f32 v71, v161, 1.0, v71 op_sel:[1,0,0] op_sel_hi:[1,0,0]
	v_fma_mix_f32 v118, v115, v115, v118 op_sel:[1,1,0] op_sel_hi:[1,1,0]
	v_fma_mix_f32 v72, v162, 1.0, v72 op_sel_hi:[1,0,0]
	v_fma_mix_f32 v118, v116, v116, v118 op_sel_hi:[1,1,0]
	v_fma_mix_f32 v73, v162, 1.0, v73 op_sel:[1,0,0] op_sel_hi:[1,0,0]
	v_fma_mix_f32 v118, v116, v116, v118 op_sel:[1,1,0] op_sel_hi:[1,1,0]
	v_fma_mix_f32 v74, v163, 1.0, v74 op_sel_hi:[1,0,0]
	v_fma_mix_f32 v118, v117, v117, v118 op_sel_hi:[1,1,0]
	v_fma_mix_f32 v75, v163, 1.0, v75 op_sel:[1,0,0] op_sel_hi:[1,0,0]
	v_fma_mix_f32 v118, v117, v117, v118 op_sel:[1,1,0] op_sel_hi:[1,1,0]
	v_cvt_pk_f16_f32 v228, v68, v69
	v_cvt_pk_f16_f32 v229, v70, v71
	v_add_f32_dpp v118, v118, v118 quad_perm:[1,0,3,2] row_mask:0xf bank_mask:0xf
	v_cvt_pk_f16_f32 v230, v72, v73
	v_cvt_pk_f16_f32 v231, v74, v75
	v_add_f32_dpp v118, v118, v118 quad_perm:[2,3,0,1] row_mask:0xf bank_mask:0xf
	global_store_dwordx4 v[236:237], v[228:231], off
	v_mov_b32_e32 v223, v222
	v_add_f32_dpp v3, v118, v118 row_half_mirror row_mask:0xf bank_mask:0xf
	s_and_saveexec_b64 s[0:1], s[100:101]
	global_store_dword v223, v3, s[2:3]
	s_or_b64 exec, exec, s[0:1]
	ds_read_b128 v[68:71], v98 offset:50688
	ds_read_b128 v[72:75], v98 offset:50704
	s_waitcnt vmcnt(15)
	s_waitcnt lgkmcnt(2)
	v_fma_mix_f32 v106, v164, 1.0, v106 op_sel_hi:[1,0,0]
	v_fma_mix_f32 v232, v228, v228, 0 op_sel:[1,1,0] op_sel_hi:[1,1,0]
	v_fma_mix_f32 v107, v164, 1.0, v107 op_sel:[1,0,0] op_sel_hi:[1,0,0]
	v_fma_mix_f32 v232, v228, v228, v232 op_sel_hi:[1,1,0]
	v_fma_mix_f32 v108, v165, 1.0, v108 op_sel_hi:[1,0,0]
	v_fma_mix_f32 v232, v229, v229, v232 op_sel_hi:[1,1,0]
	v_fma_mix_f32 v109, v165, 1.0, v109 op_sel:[1,0,0] op_sel_hi:[1,0,0]
	v_fma_mix_f32 v232, v229, v229, v232 op_sel:[1,1,0] op_sel_hi:[1,1,0]
	v_fma_mix_f32 v110, v166, 1.0, v110 op_sel_hi:[1,0,0]
	v_fma_mix_f32 v232, v230, v230, v232 op_sel_hi:[1,1,0]
	v_fma_mix_f32 v111, v166, 1.0, v111 op_sel:[1,0,0] op_sel_hi:[1,0,0]
	v_fma_mix_f32 v232, v230, v230, v232 op_sel:[1,1,0] op_sel_hi:[1,1,0]
	v_fma_mix_f32 v112, v167, 1.0, v112 op_sel_hi:[1,0,0]
	v_fma_mix_f32 v232, v231, v231, v232 op_sel_hi:[1,1,0]
	v_fma_mix_f32 v113, v167, 1.0, v113 op_sel:[1,0,0] op_sel_hi:[1,0,0]
	v_fma_mix_f32 v232, v231, v231, v232 op_sel:[1,1,0] op_sel_hi:[1,1,0]
	v_cvt_pk_f16_f32 v114, v106, v107
	v_cvt_pk_f16_f32 v115, v108, v109
	v_add_f32_dpp v232, v232, v232 quad_perm:[1,0,3,2] row_mask:0xf bank_mask:0xf
	v_cvt_pk_f16_f32 v116, v110, v111
	v_cvt_pk_f16_f32 v117, v112, v113
	v_add_f32_dpp v232, v232, v232 quad_perm:[2,3,0,1] row_mask:0xf bank_mask:0xf
	global_store_dwordx4 v[238:239], v[114:117], off
	v_add_u32_e32 v223, 0x800, v222
	v_add_f32_dpp v3, v232, v232 row_half_mirror row_mask:0xf bank_mask:0xf
	s_and_saveexec_b64 s[0:1], s[100:101]
	global_store_dword v223, v3, s[2:3]
	s_or_b64 exec, exec, s[0:1]
	ds_read_b128 v[106:109], v99
	ds_read_b128 v[110:113], v99 offset:16
	s_waitcnt vmcnt(15)
	s_waitcnt lgkmcnt(2)
; DI float h_lo(unsigned u) { return (float)__builtin_bit_cast(h2_t, u)[0]; }
; DI float h_hi(unsigned u) { return (float)__builtin_bit_cast(h2_t, u)[1]; }
; template <int EPI>
; DI void gemm_epilogue(const Ep& e, int m0, int n0) {
;     ...
;   } else if constexpr (EPI == EPI_RESID) {
; #pragma unroll
;     for (int p = 0; p < 8; ++p) {
;       const int row = p * 32 + (t >> 4), c8 = (t & 15) * 8;
;       const float4 a = *(const float4*)(T + row * 132 + c8), b = *(const float4*)(T + row * 132 + c8 + 4);
;       bf16_t* bp = e.xb + (size_t)(m0 + row) * DM + n0 + c8;
;       const uint4 xo4 = *(const uint4*)bp;
;       uint4 u;
;       u.x = pack2h(h_lo(xo4.x) + a.x, h_hi(xo4.x) + a.y); u.y = pack2h(h_lo(xo4.y) + a.z, h_hi(xo4.y) + a.w);
;       u.z = pack2h(h_lo(xo4.z) + b.x, h_hi(xo4.z) + b.y); u.w = pack2h(h_lo(xo4.w) + b.z, h_hi(xo4.w) + b.w);
;       *(uint4*)bp = u;
;       const float r0 = h_lo(u.x), r1 = h_hi(u.x), r2 = h_lo(u.y), r3 = h_hi(u.y);
;       const float r4 = h_lo(u.z), r5 = h_hi(u.z), r6 = h_lo(u.w), r7 = h_hi(u.w);
;       float s2 = r0 * r0 + r1 * r1 + r2 * r2 + r3 * r3 + r4 * r4 + r5 * r5 + r6 * r6 + r7 * r7;
;       s2 += __shfl_xor(s2, 1); s2 += __shfl_xor(s2, 2); s2 += __shfl_xor(s2, 4);
;       if ((t & 7) == 0) e.ss_out[(size_t)(m0 + row) * 16 + ((n0 + c8) >> 6)] = s2;
;     }
;     return;
	v_fma_mix_f32 v68, v168, 1.0, v68 op_sel_hi:[1,0,0]
	v_fma_mix_f32 v118, v114, v114, 0 op_sel:[1,1,0] op_sel_hi:[1,1,0]
	v_fma_mix_f32 v69, v168, 1.0, v69 op_sel:[1,0,0] op_sel_hi:[1,0,0]
	v_fma_mix_f32 v118, v114, v114, v118 op_sel_hi:[1,1,0]
	v_fma_mix_f32 v70, v169, 1.0, v70 op_sel_hi:[1,0,0]
	v_fma_mix_f32 v118, v115, v115, v118 op_sel_hi:[1,1,0]
	v_fma_mix_f32 v71, v169, 1.0, v71 op_sel:[1,0,0] op_sel_hi:[1,0,0]
	v_fma_mix_f32 v118, v115, v115, v118 op_sel:[1,1,0] op_sel_hi:[1,1,0]
	v_fma_mix_f32 v72, v170, 1.0, v72 op_sel_hi:[1,0,0]
	v_fma_mix_f32 v118, v116, v116, v118 op_sel_hi:[1,1,0]
	v_fma_mix_f32 v73, v170, 1.0, v73 op_sel:[1,0,0] op_sel_hi:[1,0,0]
	v_fma_mix_f32 v118, v116, v116, v118 op_sel:[1,1,0] op_sel_hi:[1,1,0]
	v_fma_mix_f32 v74, v171, 1.0, v74 op_sel_hi:[1,0,0]
	v_fma_mix_f32 v118, v117, v117, v118 op_sel_hi:[1,1,0]
	v_fma_mix_f32 v75, v171, 1.0, v75 op_sel:[1,0,0] op_sel_hi:[1,0,0]
	v_fma_mix_f32 v118, v117, v117, v118 op_sel:[1,1,0] op_sel_hi:[1,1,0]
	v_cvt_pk_f16_f32 v228, v68, v69
	v_cvt_pk_f16_f32 v229, v70, v71
	v_add_f32_dpp v118, v118, v118 quad_perm:[1,0,3,2] row_mask:0xf bank_mask:0xf
	v_cvt_pk_f16_f32 v230, v72, v73
	v_cvt_pk_f16_f32 v231, v74, v75
	v_add_f32_dpp v118, v118, v118 quad_perm:[2,3,0,1] row_mask:0xf bank_mask:0xf
	global_store_dwordx4 v[240:241], v[228:231], off
	v_add_u32_e32 v223, 0x1000, v222
	v_add_f32_dpp v3, v118, v118 row_half_mirror row_mask:0xf bank_mask:0xf
	s_and_saveexec_b64 s[0:1], s[100:101]
	global_store_dword v223, v3, s[2:3]
	s_or_b64 exec, exec, s[0:1]
	ds_read_b128 v[68:71], v99 offset:16896
	ds_read_b128 v[72:75], v99 offset:16912
	s_waitcnt vmcnt(15)
	s_waitcnt lgkmcnt(2)
	v_fma_mix_f32 v106, v172, 1.0, v106 op_sel_hi:[1,0,0]
	v_fma_mix_f32 v232, v228, v228, 0 op_sel:[1,1,0] op_sel_hi:[1,1,0]
	v_fma_mix_f32 v107, v172, 1.0, v107 op_sel:[1,0,0] op_sel_hi:[1,0,0]
	v_fma_mix_f32 v232, v228, v228, v232 op_sel_hi:[1,1,0]
	v_fma_mix_f32 v108, v173, 1.0, v108 op_sel_hi:[1,0,0]
	v_fma_mix_f32 v232, v229, v229, v232 op_sel_hi:[1,1,0]
	v_fma_mix_f32 v109, v173, 1.0, v109 op_sel:[1,0,0] op_sel_hi:[1,0,0]
	v_fma_mix_f32 v232, v229, v229, v232 op_sel:[1,1,0] op_sel_hi:[1,1,0]
	v_fma_mix_f32 v110, v174, 1.0, v110 op_sel_hi:[1,0,0]
	v_fma_mix_f32 v232, v230, v230, v232 op_sel_hi:[1,1,0]
	v_fma_mix_f32 v111, v174, 1.0, v111 op_sel:[1,0,0] op_sel_hi:[1,0,0]
	v_fma_mix_f32 v232, v230, v230, v232 op_sel:[1,1,0] op_sel_hi:[1,1,0]
	v_fma_mix_f32 v112, v175, 1.0, v112 op_sel_hi:[1,0,0]
	v_fma_mix_f32 v232, v231, v231, v232 op_sel_hi:[1,1,0]
	v_fma_mix_f32 v113, v175, 1.0, v113 op_sel:[1,0,0] op_sel_hi:[1,0,0]
	v_fma_mix_f32 v232, v231, v231, v232 op_sel:[1,1,0] op_sel_hi:[1,1,0]
	v_cvt_pk_f16_f32 v114, v106, v107
	v_cvt_pk_f16_f32 v115, v108, v109
	v_add_f32_dpp v232, v232, v232 quad_perm:[1,0,3,2] row_mask:0xf bank_mask:0xf
	v_cvt_pk_f16_f32 v116, v110, v111
	v_cvt_pk_f16_f32 v117, v112, v113
	v_add_f32_dpp v232, v232, v232 quad_perm:[2,3,0,1] row_mask:0xf bank_mask:0xf
	global_store_dwordx4 v[242:243], v[114:117], off
	v_add_u32_e32 v223, 0x1800, v222
	v_add_f32_dpp v3, v232, v232 row_half_mirror row_mask:0xf bank_mask:0xf
	s_and_saveexec_b64 s[0:1], s[100:101]
	global_store_dword v223, v3, s[2:3]
	s_or_b64 exec, exec, s[0:1]
	ds_read_b128 v[106:109], v99 offset:33792
	ds_read_b128 v[110:113], v99 offset:33808
	s_waitcnt vmcnt(15)
	s_waitcnt lgkmcnt(2)
	v_fma_mix_f32 v68, v176, 1.0, v68 op_sel_hi:[1,0,0]
	v_fma_mix_f32 v118, v114, v114, 0 op_sel:[1,1,0] op_sel_hi:[1,1,0]
	v_fma_mix_f32 v69, v176, 1.0, v69 op_sel:[1,0,0] op_sel_hi:[1,0,0]
	v_fma_mix_f32 v118, v114, v114, v118 op_sel_hi:[1,1,0]
	v_fma_mix_f32 v70, v177, 1.0, v70 op_sel_hi:[1,0,0]
	v_fma_mix_f32 v118, v115, v115, v118 op_sel_hi:[1,1,0]
	v_fma_mix_f32 v71, v177, 1.0, v71 op_sel:[1,0,0] op_sel_hi:[1,0,0]
	v_fma_mix_f32 v118, v115, v115, v118 op_sel:[1,1,0] op_sel_hi:[1,1,0]
	v_fma_mix_f32 v72, v178, 1.0, v72 op_sel_hi:[1,0,0]
	v_fma_mix_f32 v118, v116, v116, v118 op_sel_hi:[1,1,0]
	v_fma_mix_f32 v73, v178, 1.0, v73 op_sel:[1,0,0] op_sel_hi:[1,0,0]
	v_fma_mix_f32 v118, v116, v116, v118 op_sel:[1,1,0] op_sel_hi:[1,1,0]
	v_fma_mix_f32 v74, v179, 1.0, v74 op_sel_hi:[1,0,0]
	v_fma_mix_f32 v118, v117, v117, v118 op_sel_hi:[1,1,0]
	v_fma_mix_f32 v75, v179, 1.0, v75 op_sel:[1,0,0] op_sel_hi:[1,0,0]
	v_fma_mix_f32 v118, v117, v117, v118 op_sel:[1,1,0] op_sel_hi:[1,1,0]
	v_cvt_pk_f16_f32 v228, v68, v69
	v_cvt_pk_f16_f32 v229, v70, v71
	v_add_f32_dpp v118, v118, v118 quad_perm:[1,0,3,2] row_mask:0xf bank_mask:0xf
	v_cvt_pk_f16_f32 v230, v72, v73
	v_cvt_pk_f16_f32 v231, v74, v75
	v_add_f32_dpp v118, v118, v118 quad_perm:[2,3,0,1] row_mask:0xf bank_mask:0xf
	global_store_dwordx4 v[244:245], v[228:231], off
	v_add_u32_e32 v223, 0x2000, v222
	v_add_f32_dpp v3, v118, v118 row_half_mirror row_mask:0xf bank_mask:0xf
	s_and_saveexec_b64 s[0:1], s[100:101]
	global_store_dword v223, v3, s[2:3]
	s_or_b64 exec, exec, s[0:1]
	ds_read_b128 v[68:71], v99 offset:50688
	ds_read_b128 v[72:75], v99 offset:50704
	s_waitcnt vmcnt(15)
	s_waitcnt lgkmcnt(2)
; DI float h_lo(unsigned u) { return (float)__builtin_bit_cast(h2_t, u)[0]; }
; DI float h_hi(unsigned u) { return (float)__builtin_bit_cast(h2_t, u)[1]; }
; template <int EPI>
; DI void gemm_epilogue(const Ep& e, int m0, int n0) {
;     ...
;   } else if constexpr (EPI == EPI_RESID) {
; #pragma unroll
;     for (int p = 0; p < 8; ++p) {
;       const int row = p * 32 + (t >> 4), c8 = (t & 15) * 8;
;       const float4 a = *(const float4*)(T + row * 132 + c8), b = *(const float4*)(T + row * 132 + c8 + 4);
;       bf16_t* bp = e.xb + (size_t)(m0 + row) * DM + n0 + c8;
;       const uint4 xo4 = *(const uint4*)bp;
;       uint4 u;
;       u.x = pack2h(h_lo(xo4.x) + a.x, h_hi(xo4.x) + a.y); u.y = pack2h(h_lo(xo4.y) + a.z, h_hi(xo4.y) + a.w);
;       u.z = pack2h(h_lo(xo4.z) + b.x, h_hi(xo4.z) + b.y); u.w = pack2h(h_lo(xo4.w) + b.z, h_hi(xo4.w) + b.w);
;       *(uint4*)bp = u;
;       const float r0 = h_lo(u.x), r1 = h_hi(u.x), r2 = h_lo(u.y), r3 = h_hi(u.y);
;       const float r4 = h_lo(u.z), r5 = h_hi(u.z), r6 = h_lo(u.w), r7 = h_hi(u.w);
;       float s2 = r0 * r0 + r1 * r1 + r2 * r2 + r3 * r3 + r4 * r4 + r5 * r5 + r6 * r6 + r7 * r7;
;       s2 += __shfl_xor(s2, 1); s2 += __shfl_xor(s2, 2); s2 += __shfl_xor(s2, 4);
;       if ((t & 7) == 0) e.ss_out[(size_t)(m0 + row) * 16 + ((n0 + c8) >> 6)] = s2;
;     }
;     return;
;     ...
;   float* T = (float*)smem;
; #pragma unroll
;   for (int bj = 0; bj < 2; ++bj) {
; #pragma unroll
;     for (int ai = 0; ai < 2; ++ai)
; #pragma unroll
;       for (int m = 0; m < 4; ++m)
; #pragma unroll
;         for (int n = 0; n < 2; ++n)
; #pragma unroll
;           for (int j = 0; j < 4; ++j)
;             T[(ai * 128 + wr * 64 + m * 16 + fq * 4 + j) * 132 + wc * 32 + n * 16 + fr] = acc[ai][bj][m][n][j];
;     __syncthreads();
	v_fma_mix_f32 v106, v180, 1.0, v106 op_sel_hi:[1,0,0]
	v_fma_mix_f32 v232, v228, v228, 0 op_sel:[1,1,0] op_sel_hi:[1,1,0]
	v_fma_mix_f32 v107, v180, 1.0, v107 op_sel:[1,0,0] op_sel_hi:[1,0,0]
	v_fma_mix_f32 v232, v228, v228, v232 op_sel_hi:[1,1,0]
	v_fma_mix_f32 v108, v181, 1.0, v108 op_sel_hi:[1,0,0]
	v_fma_mix_f32 v232, v229, v229, v232 op_sel_hi:[1,1,0]
	v_fma_mix_f32 v109, v181, 1.0, v109 op_sel:[1,0,0] op_sel_hi:[1,0,0]
	v_fma_mix_f32 v232, v229, v229, v232 op_sel:[1,1,0] op_sel_hi:[1,1,0]
	v_fma_mix_f32 v110, v182, 1.0, v110 op_sel_hi:[1,0,0]
	v_fma_mix_f32 v232, v230, v230, v232 op_sel_hi:[1,1,0]
	v_fma_mix_f32 v111, v182, 1.0, v111 op_sel:[1,0,0] op_sel_hi:[1,0,0]
	v_fma_mix_f32 v232, v230, v230, v232 op_sel:[1,1,0] op_sel_hi:[1,1,0]
	v_fma_mix_f32 v112, v183, 1.0, v112 op_sel_hi:[1,0,0]
	v_fma_mix_f32 v232, v231, v231, v232 op_sel_hi:[1,1,0]
	v_fma_mix_f32 v113, v183, 1.0, v113 op_sel:[1,0,0] op_sel_hi:[1,0,0]
	v_fma_mix_f32 v232, v231, v231, v232 op_sel:[1,1,0] op_sel_hi:[1,1,0]
	v_cvt_pk_f16_f32 v114, v106, v107
	v_cvt_pk_f16_f32 v115, v108, v109
	v_add_f32_dpp v232, v232, v232 quad_perm:[1,0,3,2] row_mask:0xf bank_mask:0xf
	v_cvt_pk_f16_f32 v116, v110, v111
	v_cvt_pk_f16_f32 v117, v112, v113
	v_add_f32_dpp v232, v232, v232 quad_perm:[2,3,0,1] row_mask:0xf bank_mask:0xf
	global_store_dwordx4 v[246:247], v[114:117], off
	v_add_u32_e32 v223, 0x2800, v222
	v_add_f32_dpp v3, v232, v232 row_half_mirror row_mask:0xf bank_mask:0xf
	s_and_saveexec_b64 s[0:1], s[100:101]
	global_store_dword v223, v3, s[2:3]
	s_or_b64 exec, exec, s[0:1]
	s_waitcnt vmcnt(15)
	s_waitcnt lgkmcnt(0)
	v_fma_mix_f32 v68, v184, 1.0, v68 op_sel_hi:[1,0,0]
	v_fma_mix_f32 v118, v114, v114, 0 op_sel:[1,1,0] op_sel_hi:[1,1,0]
	v_fma_mix_f32 v69, v184, 1.0, v69 op_sel:[1,0,0] op_sel_hi:[1,0,0]
	v_fma_mix_f32 v118, v114, v114, v118 op_sel_hi:[1,1,0]
	v_fma_mix_f32 v70, v185, 1.0, v70 op_sel_hi:[1,0,0]
	v_fma_mix_f32 v118, v115, v115, v118 op_sel_hi:[1,1,0]
	v_fma_mix_f32 v71, v185, 1.0, v71 op_sel:[1,0,0] op_sel_hi:[1,0,0]
	v_fma_mix_f32 v118, v115, v115, v118 op_sel:[1,1,0] op_sel_hi:[1,1,0]
	v_fma_mix_f32 v72, v186, 1.0, v72 op_sel_hi:[1,0,0]
	v_fma_mix_f32 v118, v116, v116, v118 op_sel_hi:[1,1,0]
	v_fma_mix_f32 v73, v186, 1.0, v73 op_sel:[1,0,0] op_sel_hi:[1,0,0]
	v_fma_mix_f32 v118, v116, v116, v118 op_sel:[1,1,0] op_sel_hi:[1,1,0]
	v_fma_mix_f32 v74, v187, 1.0, v74 op_sel_hi:[1,0,0]
	v_fma_mix_f32 v118, v117, v117, v118 op_sel_hi:[1,1,0]
	v_fma_mix_f32 v75, v187, 1.0, v75 op_sel:[1,0,0] op_sel_hi:[1,0,0]
	v_fma_mix_f32 v118, v117, v117, v118 op_sel:[1,1,0] op_sel_hi:[1,1,0]
	v_cvt_pk_f16_f32 v228, v68, v69
	v_cvt_pk_f16_f32 v229, v70, v71
	v_add_f32_dpp v118, v118, v118 quad_perm:[1,0,3,2] row_mask:0xf bank_mask:0xf
	v_cvt_pk_f16_f32 v230, v72, v73
	v_cvt_pk_f16_f32 v231, v74, v75
	v_add_f32_dpp v118, v118, v118 quad_perm:[2,3,0,1] row_mask:0xf bank_mask:0xf
	global_store_dwordx4 v[248:249], v[228:231], off
	v_add_u32_e32 v223, 0x3000, v222
	v_add_f32_dpp v3, v118, v118 row_half_mirror row_mask:0xf bank_mask:0xf
	s_and_saveexec_b64 s[0:1], s[100:101]
	global_store_dword v223, v3, s[2:3]
	s_or_b64 exec, exec, s[0:1]
	v_fma_mix_f32 v232, v228, v228, 0 op_sel:[1,1,0] op_sel_hi:[1,1,0]
	s_nop 0
	v_fma_mix_f32 v232, v228, v228, v232 op_sel_hi:[1,1,0]
	s_nop 0
	v_fma_mix_f32 v232, v229, v229, v232 op_sel_hi:[1,1,0]
	s_nop 0
	v_fma_mix_f32 v232, v229, v229, v232 op_sel:[1,1,0] op_sel_hi:[1,1,0]
	s_nop 0
	v_fma_mix_f32 v232, v230, v230, v232 op_sel_hi:[1,1,0]
	s_nop 0
	v_fma_mix_f32 v232, v230, v230, v232 op_sel:[1,1,0] op_sel_hi:[1,1,0]
	s_nop 0
	v_fma_mix_f32 v232, v231, v231, v232 op_sel_hi:[1,1,0]
	s_nop 0
	v_fma_mix_f32 v232, v231, v231, v232 op_sel:[1,1,0] op_sel_hi:[1,1,0]
	s_nop 1
	v_add_f32_dpp v232, v232, v232 quad_perm:[1,0,3,2] row_mask:0xf bank_mask:0xf
	s_nop 1
	v_add_f32_dpp v232, v232, v232 quad_perm:[2,3,0,1] row_mask:0xf bank_mask:0xf
	v_add_u32_e32 v223, 0x3800, v222
	s_nop 0
	v_add_f32_dpp v3, v232, v232 row_half_mirror row_mask:0xf bank_mask:0xf
	s_and_saveexec_b64 s[0:1], s[100:101]
	global_store_dword v223, v3, s[2:3]
	s_or_b64 exec, exec, s[0:1]
.LBB0_929:
	s_or_b64 exec, exec, s[0:1]
	s_waitcnt lgkmcnt(0)
	s_barrier
	ds_write2_b32 v132, v4, v20 offset1:16
	ds_write2_b32 v132, v5, v21 offset0:132 offset1:148
	ds_write2_b32 v104, v6, v22 offset0:8 offset1:24
	ds_write2_b32 v104, v7, v23 offset0:140 offset1:156
	ds_write2_b32 v105, v8, v24 offset0:64 offset1:80
	ds_write2_b32 v105, v9, v25 offset0:196 offset1:212
	ds_write2_b32 v100, v10, v26 offset0:72 offset1:88
	ds_write2_b32 v100, v11, v27 offset0:204 offset1:220
	ds_write2_b32 v101, v12, v28 offset0:128 offset1:144
	ds_write2_b32 v92, v13, v29 offset0:4 offset1:20
	ds_write2_b32 v92, v14, v30 offset0:136 offset1:152
	ds_write2_b32 v93, v15, v31 offset0:12 offset1:28
	ds_write2_b32 v94, v16, v32 offset0:192 offset1:208
	ds_write2_b32 v84, v17, v33 offset0:68 offset1:84
	ds_write2_b32 v84, v18, v34 offset0:200 offset1:216
	ds_write2_b32 v85, v19, v35 offset0:76 offset1:92
	ds_write2_b32 v86, v36, v52 offset1:16
	ds_write2_b32 v87, v37, v53 offset1:16
	ds_write2_b32 v88, v38, v54 offset1:16
	ds_write2_b32 v89, v39, v55 offset1:16
	ds_write2_b32 v90, v40, v56 offset1:16
	ds_write2_b32 v91, v41, v57 offset1:16
	ds_write2_b32 v95, v42, v58 offset1:16
	ds_write2_b32 v96, v43, v59 offset1:16
	ds_write2_b32 v97, v44, v60 offset1:16
	ds_write2_b32 v80, v45, v61 offset1:16
	ds_write2_b32 v81, v46, v62 offset1:16
	ds_write2_b32 v82, v47, v63 offset1:16
	ds_write2_b32 v76, v48, v64 offset1:16
	ds_write2_b32 v77, v49, v65 offset1:16
	ds_write2_b32 v78, v50, v66 offset1:16
	ds_write2_b32 v79, v51, v67 offset1:16
	v_mov_b32_e32 v9, v224
	s_waitcnt lgkmcnt(0)
	s_barrier
; DI float h_lo(unsigned u) { return (float)__builtin_bit_cast(h2_t, u)[0]; }
; DI float h_hi(unsigned u) { return (float)__builtin_bit_cast(h2_t, u)[1]; }
; template <int EPI>
; DI void gemm_epilogue(const Ep& e, int m0, int n0) {
;     ...
;   } else if constexpr (EPI == EPI_RESID) {
; #pragma unroll
;     for (int p = 0; p < 8; ++p) {
;       const int row = p * 32 + (t >> 4), c8 = (t & 15) * 8;
;       const float4 a = *(const float4*)(T + row * 132 + c8), b = *(const float4*)(T + row * 132 + c8 + 4);
;       bf16_t* bp = e.xb + (size_t)(m0 + row) * DM + n0 + c8;
;       const uint4 xo4 = *(const uint4*)bp;
;       uint4 u;
;       u.x = pack2h(h_lo(xo4.x) + a.x, h_hi(xo4.x) + a.y); u.y = pack2h(h_lo(xo4.y) + a.z, h_hi(xo4.y) + a.w);
;       u.z = pack2h(h_lo(xo4.z) + b.x, h_hi(xo4.z) + b.y); u.w = pack2h(h_lo(xo4.w) + b.z, h_hi(xo4.w) + b.w);
;       *(uint4*)bp = u;
;       const float r0 = h_lo(u.x), r1 = h_hi(u.x), r2 = h_lo(u.y), r3 = h_hi(u.y);
;       const float r4 = h_lo(u.z), r5 = h_hi(u.z), r6 = h_lo(u.w), r7 = h_hi(u.w);
;       float s2 = r0 * r0 + r1 * r1 + r2 * r2 + r3 * r3 + r4 * r4 + r5 * r5 + r6 * r6 + r7 * r7;
;       s2 += __shfl_xor(s2, 1); s2 += __shfl_xor(s2, 2); s2 += __shfl_xor(s2, 4);
;       if ((t & 7) == 0) e.ss_out[(size_t)(m0 + row) * 16 + ((n0 + c8) >> 6)] = s2;
;     }
;     return;
	v_lshrrev_b32_e32 v220, 4, v224
	v_and_b32_e32 v221, 15, v224
	v_lshlrev_b32_e32 v221, 3, v221
	v_or_b32_e32 v221, s30, v221
	v_ashrrev_i32_e32 v221, 6, v221
	v_add_u32_e32 v220, s25, v220
	v_lshlrev_b32_e32 v220, 6, v220
	v_lshl_add_u32 v222, v221, 2, v220
	ds_read_b128 v[106:109], v98
	ds_read_b128 v[110:113], v98 offset:16
	ds_read_b128 v[68:71], v98 offset:16896
	ds_read_b128 v[72:75], v98 offset:16912
	s_waitcnt vmcnt(15)
	s_waitcnt lgkmcnt(2)
	v_fma_mix_f32 v106, v188, 1.0, v106 op_sel_hi:[1,0,0]
	v_fma_mix_f32 v107, v188, 1.0, v107 op_sel:[1,0,0] op_sel_hi:[1,0,0]
	v_fma_mix_f32 v108, v189, 1.0, v108 op_sel_hi:[1,0,0]
	v_fma_mix_f32 v109, v189, 1.0, v109 op_sel:[1,0,0] op_sel_hi:[1,0,0]
	v_fma_mix_f32 v110, v190, 1.0, v110 op_sel_hi:[1,0,0]
	v_fma_mix_f32 v111, v190, 1.0, v111 op_sel:[1,0,0] op_sel_hi:[1,0,0]
	v_fma_mix_f32 v112, v191, 1.0, v112 op_sel_hi:[1,0,0]
	v_fma_mix_f32 v113, v191, 1.0, v113 op_sel:[1,0,0] op_sel_hi:[1,0,0]
	v_cvt_pk_f16_f32 v114, v106, v107
	v_cvt_pk_f16_f32 v115, v108, v109
	v_cvt_pk_f16_f32 v116, v110, v111
	v_cvt_pk_f16_f32 v117, v112, v113
	global_store_dwordx4 v[250:251], v[114:117], off offset:256
	ds_read_b128 v[106:109], v98 offset:33792
	ds_read_b128 v[110:113], v98 offset:33808
	s_waitcnt vmcnt(15)
	s_waitcnt lgkmcnt(2)
	v_fma_mix_f32 v68, v192, 1.0, v68 op_sel_hi:[1,0,0]
	v_fma_mix_f32 v118, v114, v114, 0 op_sel:[1,1,0] op_sel_hi:[1,1,0]
	v_fma_mix_f32 v69, v192, 1.0, v69 op_sel:[1,0,0] op_sel_hi:[1,0,0]
	v_fma_mix_f32 v118, v114, v114, v118 op_sel_hi:[1,1,0]
	v_fma_mix_f32 v70, v193, 1.0, v70 op_sel_hi:[1,0,0]
	v_fma_mix_f32 v118, v115, v115, v118 op_sel_hi:[1,1,0]
	v_fma_mix_f32 v71, v193, 1.0, v71 op_sel:[1,0,0] op_sel_hi:[1,0,0]
	v_fma_mix_f32 v118, v115, v115, v118 op_sel:[1,1,0] op_sel_hi:[1,1,0]
	v_fma_mix_f32 v72, v194, 1.0, v72 op_sel_hi:[1,0,0]
	v_fma_mix_f32 v118, v116, v116, v118 op_sel_hi:[1,1,0]
	v_fma_mix_f32 v73, v194, 1.0, v73 op_sel:[1,0,0] op_sel_hi:[1,0,0]
	v_fma_mix_f32 v118, v116, v116, v118 op_sel:[1,1,0] op_sel_hi:[1,1,0]
	v_fma_mix_f32 v74, v195, 1.0, v74 op_sel_hi:[1,0,0]
	v_fma_mix_f32 v118, v117, v117, v118 op_sel_hi:[1,1,0]
	v_fma_mix_f32 v75, v195, 1.0, v75 op_sel:[1,0,0] op_sel_hi:[1,0,0]
	v_fma_mix_f32 v118, v117, v117, v118 op_sel:[1,1,0] op_sel_hi:[1,1,0]
	v_cvt_pk_f16_f32 v228, v68, v69
	v_cvt_pk_f16_f32 v229, v70, v71
	v_add_f32_dpp v118, v118, v118 quad_perm:[1,0,3,2] row_mask:0xf bank_mask:0xf
	v_cvt_pk_f16_f32 v230, v72, v73
	v_cvt_pk_f16_f32 v231, v74, v75
	v_add_f32_dpp v118, v118, v118 quad_perm:[2,3,0,1] row_mask:0xf bank_mask:0xf
	global_store_dwordx4 v[236:237], v[228:231], off offset:256
	v_mov_b32_e32 v223, v222
	v_add_f32_dpp v3, v118, v118 row_half_mirror row_mask:0xf bank_mask:0xf
	s_and_saveexec_b64 s[0:1], s[100:101]
	global_store_dword v223, v3, s[2:3]
	s_or_b64 exec, exec, s[0:1]
	ds_read_b128 v[68:71], v98 offset:50688
	ds_read_b128 v[72:75], v98 offset:50704
	s_waitcnt vmcnt(15)
	s_waitcnt lgkmcnt(2)
	v_fma_mix_f32 v106, v196, 1.0, v106 op_sel_hi:[1,0,0]
	v_fma_mix_f32 v232, v228, v228, 0 op_sel:[1,1,0] op_sel_hi:[1,1,0]
	v_fma_mix_f32 v107, v196, 1.0, v107 op_sel:[1,0,0] op_sel_hi:[1,0,0]
	v_fma_mix_f32 v232, v228, v228, v232 op_sel_hi:[1,1,0]
	v_fma_mix_f32 v108, v197, 1.0, v108 op_sel_hi:[1,0,0]
	v_fma_mix_f32 v232, v229, v229, v232 op_sel_hi:[1,1,0]
	v_fma_mix_f32 v109, v197, 1.0, v109 op_sel:[1,0,0] op_sel_hi:[1,0,0]
	v_fma_mix_f32 v232, v229, v229, v232 op_sel:[1,1,0] op_sel_hi:[1,1,0]
	v_fma_mix_f32 v110, v198, 1.0, v110 op_sel_hi:[1,0,0]
	v_fma_mix_f32 v232, v230, v230, v232 op_sel_hi:[1,1,0]
	v_fma_mix_f32 v111, v198, 1.0, v111 op_sel:[1,0,0] op_sel_hi:[1,0,0]
	v_fma_mix_f32 v232, v230, v230, v232 op_sel:[1,1,0] op_sel_hi:[1,1,0]
	v_fma_mix_f32 v112, v199, 1.0, v112 op_sel_hi:[1,0,0]
	v_fma_mix_f32 v232, v231, v231, v232 op_sel_hi:[1,1,0]
	v_fma_mix_f32 v113, v199, 1.0, v113 op_sel:[1,0,0] op_sel_hi:[1,0,0]
	v_fma_mix_f32 v232, v231, v231, v232 op_sel:[1,1,0] op_sel_hi:[1,1,0]
	v_cvt_pk_f16_f32 v114, v106, v107
	v_cvt_pk_f16_f32 v115, v108, v109
	v_add_f32_dpp v232, v232, v232 quad_perm:[1,0,3,2] row_mask:0xf bank_mask:0xf
	v_cvt_pk_f16_f32 v116, v110, v111
	v_cvt_pk_f16_f32 v117, v112, v113
	v_add_f32_dpp v232, v232, v232 quad_perm:[2,3,0,1] row_mask:0xf bank_mask:0xf
	global_store_dwordx4 v[238:239], v[114:117], off offset:256
	v_add_u32_e32 v223, 0x800, v222
	v_add_f32_dpp v3, v232, v232 row_half_mirror row_mask:0xf bank_mask:0xf
	s_and_saveexec_b64 s[0:1], s[100:101]
	global_store_dword v223, v3, s[2:3]
	s_or_b64 exec, exec, s[0:1]
	ds_read_b128 v[106:109], v99
	ds_read_b128 v[110:113], v99 offset:16
	s_waitcnt vmcnt(15)
	s_waitcnt lgkmcnt(2)
	v_fma_mix_f32 v68, v200, 1.0, v68 op_sel_hi:[1,0,0]
	v_fma_mix_f32 v118, v114, v114, 0 op_sel:[1,1,0] op_sel_hi:[1,1,0]
	v_fma_mix_f32 v69, v200, 1.0, v69 op_sel:[1,0,0] op_sel_hi:[1,0,0]
	v_fma_mix_f32 v118, v114, v114, v118 op_sel_hi:[1,1,0]
	v_fma_mix_f32 v70, v201, 1.0, v70 op_sel_hi:[1,0,0]
	v_fma_mix_f32 v118, v115, v115, v118 op_sel_hi:[1,1,0]
	v_fma_mix_f32 v71, v201, 1.0, v71 op_sel:[1,0,0] op_sel_hi:[1,0,0]
	v_fma_mix_f32 v118, v115, v115, v118 op_sel:[1,1,0] op_sel_hi:[1,1,0]
	v_fma_mix_f32 v72, v202, 1.0, v72 op_sel_hi:[1,0,0]
	v_fma_mix_f32 v118, v116, v116, v118 op_sel_hi:[1,1,0]
	v_fma_mix_f32 v73, v202, 1.0, v73 op_sel:[1,0,0] op_sel_hi:[1,0,0]
	v_fma_mix_f32 v118, v116, v116, v118 op_sel:[1,1,0] op_sel_hi:[1,1,0]
	v_fma_mix_f32 v74, v203, 1.0, v74 op_sel_hi:[1,0,0]
	v_fma_mix_f32 v118, v117, v117, v118 op_sel_hi:[1,1,0]
	v_fma_mix_f32 v75, v203, 1.0, v75 op_sel:[1,0,0] op_sel_hi:[1,0,0]
	v_fma_mix_f32 v118, v117, v117, v118 op_sel:[1,1,0] op_sel_hi:[1,1,0]
	v_cvt_pk_f16_f32 v228, v68, v69
	v_cvt_pk_f16_f32 v229, v70, v71
	v_add_f32_dpp v118, v118, v118 quad_perm:[1,0,3,2] row_mask:0xf bank_mask:0xf
	v_cvt_pk_f16_f32 v230, v72, v73
	v_cvt_pk_f16_f32 v231, v74, v75
	v_add_f32_dpp v118, v118, v118 quad_perm:[2,3,0,1] row_mask:0xf bank_mask:0xf
	global_store_dwordx4 v[240:241], v[228:231], off offset:256
	v_add_u32_e32 v223, 0x1000, v222
	v_add_f32_dpp v3, v118, v118 row_half_mirror row_mask:0xf bank_mask:0xf
	s_and_saveexec_b64 s[0:1], s[100:101]
	global_store_dword v223, v3, s[2:3]
	s_or_b64 exec, exec, s[0:1]
	ds_read_b128 v[68:71], v99 offset:16896
	ds_read_b128 v[72:75], v99 offset:16912
	s_waitcnt vmcnt(15)
; DI float h_lo(unsigned u) { return (float)__builtin_bit_cast(h2_t, u)[0]; }
; DI float h_hi(unsigned u) { return (float)__builtin_bit_cast(h2_t, u)[1]; }
; template <int EPI>
; DI void gemm_epilogue(const Ep& e, int m0, int n0) {
;     ...
;   } else if constexpr (EPI == EPI_RESID) {
; #pragma unroll
;     for (int p = 0; p < 8; ++p) {
;       const int row = p * 32 + (t >> 4), c8 = (t & 15) * 8;
;       const float4 a = *(const float4*)(T + row * 132 + c8), b = *(const float4*)(T + row * 132 + c8 + 4);
;       bf16_t* bp = e.xb + (size_t)(m0 + row) * DM + n0 + c8;
;       const uint4 xo4 = *(const uint4*)bp;
;       uint4 u;
;       u.x = pack2h(h_lo(xo4.x) + a.x, h_hi(xo4.x) + a.y); u.y = pack2h(h_lo(xo4.y) + a.z, h_hi(xo4.y) + a.w);
;       u.z = pack2h(h_lo(xo4.z) + b.x, h_hi(xo4.z) + b.y); u.w = pack2h(h_lo(xo4.w) + b.z, h_hi(xo4.w) + b.w);
;       *(uint4*)bp = u;
;       const float r0 = h_lo(u.x), r1 = h_hi(u.x), r2 = h_lo(u.y), r3 = h_hi(u.y);
;       const float r4 = h_lo(u.z), r5 = h_hi(u.z), r6 = h_lo(u.w), r7 = h_hi(u.w);
;       float s2 = r0 * r0 + r1 * r1 + r2 * r2 + r3 * r3 + r4 * r4 + r5 * r5 + r6 * r6 + r7 * r7;
;       s2 += __shfl_xor(s2, 1); s2 += __shfl_xor(s2, 2); s2 += __shfl_xor(s2, 4);
;       if ((t & 7) == 0) e.ss_out[(size_t)(m0 + row) * 16 + ((n0 + c8) >> 6)] = s2;
;     }
;     return;
	s_waitcnt lgkmcnt(2)
	v_fma_mix_f32 v106, v204, 1.0, v106 op_sel_hi:[1,0,0]
	v_fma_mix_f32 v232, v228, v228, 0 op_sel:[1,1,0] op_sel_hi:[1,1,0]
	v_fma_mix_f32 v107, v204, 1.0, v107 op_sel:[1,0,0] op_sel_hi:[1,0,0]
	v_fma_mix_f32 v232, v228, v228, v232 op_sel_hi:[1,1,0]
	v_fma_mix_f32 v108, v205, 1.0, v108 op_sel_hi:[1,0,0]
	v_fma_mix_f32 v232, v229, v229, v232 op_sel_hi:[1,1,0]
	v_fma_mix_f32 v109, v205, 1.0, v109 op_sel:[1,0,0] op_sel_hi:[1,0,0]
	v_fma_mix_f32 v232, v229, v229, v232 op_sel:[1,1,0] op_sel_hi:[1,1,0]
	v_fma_mix_f32 v110, v206, 1.0, v110 op_sel_hi:[1,0,0]
	v_fma_mix_f32 v232, v230, v230, v232 op_sel_hi:[1,1,0]
	v_fma_mix_f32 v111, v206, 1.0, v111 op_sel:[1,0,0] op_sel_hi:[1,0,0]
	v_fma_mix_f32 v232, v230, v230, v232 op_sel:[1,1,0] op_sel_hi:[1,1,0]
	v_fma_mix_f32 v112, v207, 1.0, v112 op_sel_hi:[1,0,0]
	v_fma_mix_f32 v232, v231, v231, v232 op_sel_hi:[1,1,0]
	v_fma_mix_f32 v113, v207, 1.0, v113 op_sel:[1,0,0] op_sel_hi:[1,0,0]
	v_fma_mix_f32 v232, v231, v231, v232 op_sel:[1,1,0] op_sel_hi:[1,1,0]
	v_cvt_pk_f16_f32 v114, v106, v107
	v_cvt_pk_f16_f32 v115, v108, v109
	v_add_f32_dpp v232, v232, v232 quad_perm:[1,0,3,2] row_mask:0xf bank_mask:0xf
	v_cvt_pk_f16_f32 v116, v110, v111
	v_cvt_pk_f16_f32 v117, v112, v113
	v_add_f32_dpp v232, v232, v232 quad_perm:[2,3,0,1] row_mask:0xf bank_mask:0xf
	global_store_dwordx4 v[242:243], v[114:117], off offset:256
	v_add_u32_e32 v223, 0x1800, v222
	v_add_f32_dpp v3, v232, v232 row_half_mirror row_mask:0xf bank_mask:0xf
	s_and_saveexec_b64 s[0:1], s[100:101]
	global_store_dword v223, v3, s[2:3]
	s_or_b64 exec, exec, s[0:1]
	ds_read_b128 v[106:109], v99 offset:33792
	ds_read_b128 v[110:113], v99 offset:33808
	s_waitcnt vmcnt(15)
	s_waitcnt lgkmcnt(2)
	v_fma_mix_f32 v68, v208, 1.0, v68 op_sel_hi:[1,0,0]
	v_fma_mix_f32 v118, v114, v114, 0 op_sel:[1,1,0] op_sel_hi:[1,1,0]
	v_fma_mix_f32 v69, v208, 1.0, v69 op_sel:[1,0,0] op_sel_hi:[1,0,0]
	v_fma_mix_f32 v118, v114, v114, v118 op_sel_hi:[1,1,0]
	v_fma_mix_f32 v70, v209, 1.0, v70 op_sel_hi:[1,0,0]
	v_fma_mix_f32 v118, v115, v115, v118 op_sel_hi:[1,1,0]
	v_fma_mix_f32 v71, v209, 1.0, v71 op_sel:[1,0,0] op_sel_hi:[1,0,0]
	v_fma_mix_f32 v118, v115, v115, v118 op_sel:[1,1,0] op_sel_hi:[1,1,0]
	v_fma_mix_f32 v72, v210, 1.0, v72 op_sel_hi:[1,0,0]
	v_fma_mix_f32 v118, v116, v116, v118 op_sel_hi:[1,1,0]
	v_fma_mix_f32 v73, v210, 1.0, v73 op_sel:[1,0,0] op_sel_hi:[1,0,0]
	v_fma_mix_f32 v118, v116, v116, v118 op_sel:[1,1,0] op_sel_hi:[1,1,0]
	v_fma_mix_f32 v74, v211, 1.0, v74 op_sel_hi:[1,0,0]
	v_fma_mix_f32 v118, v117, v117, v118 op_sel_hi:[1,1,0]
	v_fma_mix_f32 v75, v211, 1.0, v75 op_sel:[1,0,0] op_sel_hi:[1,0,0]
	v_fma_mix_f32 v118, v117, v117, v118 op_sel:[1,1,0] op_sel_hi:[1,1,0]
	v_cvt_pk_f16_f32 v228, v68, v69
	v_cvt_pk_f16_f32 v229, v70, v71
	v_add_f32_dpp v118, v118, v118 quad_perm:[1,0,3,2] row_mask:0xf bank_mask:0xf
	v_cvt_pk_f16_f32 v230, v72, v73
	v_cvt_pk_f16_f32 v231, v74, v75
	v_add_f32_dpp v118, v118, v118 quad_perm:[2,3,0,1] row_mask:0xf bank_mask:0xf
	global_store_dwordx4 v[244:245], v[228:231], off offset:256
	v_add_u32_e32 v223, 0x2000, v222
	v_add_f32_dpp v3, v118, v118 row_half_mirror row_mask:0xf bank_mask:0xf
	s_and_saveexec_b64 s[0:1], s[100:101]
	global_store_dword v223, v3, s[2:3]
	s_or_b64 exec, exec, s[0:1]
	ds_read_b128 v[68:71], v99 offset:50688
	ds_read_b128 v[72:75], v99 offset:50704
	s_waitcnt vmcnt(15)
	s_waitcnt lgkmcnt(2)
; DI float h_lo(unsigned u) { return (float)__builtin_bit_cast(h2_t, u)[0]; }
; DI float h_hi(unsigned u) { return (float)__builtin_bit_cast(h2_t, u)[1]; }
; template <int EPI>
; DI void gemm_epilogue(const Ep& e, int m0, int n0) {
;     ...
;   } else if constexpr (EPI == EPI_RESID) {
; #pragma unroll
;     for (int p = 0; p < 8; ++p) {
;       const int row = p * 32 + (t >> 4), c8 = (t & 15) * 8;
;       const float4 a = *(const float4*)(T + row * 132 + c8), b = *(const float4*)(T + row * 132 + c8 + 4);
;       bf16_t* bp = e.xb + (size_t)(m0 + row) * DM + n0 + c8;
;       const uint4 xo4 = *(const uint4*)bp;
;       uint4 u;
;       u.x = pack2h(h_lo(xo4.x) + a.x, h_hi(xo4.x) + a.y); u.y = pack2h(h_lo(xo4.y) + a.z, h_hi(xo4.y) + a.w);
;       u.z = pack2h(h_lo(xo4.z) + b.x, h_hi(xo4.z) + b.y); u.w = pack2h(h_lo(xo4.w) + b.z, h_hi(xo4.w) + b.w);
;       *(uint4*)bp = u;
;       const float r0 = h_lo(u.x), r1 = h_hi(u.x), r2 = h_lo(u.y), r3 = h_hi(u.y);
;       const float r4 = h_lo(u.z), r5 = h_hi(u.z), r6 = h_lo(u.w), r7 = h_hi(u.w);
;       float s2 = r0 * r0 + r1 * r1 + r2 * r2 + r3 * r3 + r4 * r4 + r5 * r5 + r6 * r6 + r7 * r7;
;       s2 += __shfl_xor(s2, 1); s2 += __shfl_xor(s2, 2); s2 += __shfl_xor(s2, 4);
;       if ((t & 7) == 0) e.ss_out[(size_t)(m0 + row) * 16 + ((n0 + c8) >> 6)] = s2;
;     }
;     return;
	v_fma_mix_f32 v106, v212, 1.0, v106 op_sel_hi:[1,0,0]
	v_fma_mix_f32 v232, v228, v228, 0 op_sel:[1,1,0] op_sel_hi:[1,1,0]
	v_fma_mix_f32 v107, v212, 1.0, v107 op_sel:[1,0,0] op_sel_hi:[1,0,0]
	v_fma_mix_f32 v232, v228, v228, v232 op_sel_hi:[1,1,0]
	v_fma_mix_f32 v108, v213, 1.0, v108 op_sel_hi:[1,0,0]
	v_fma_mix_f32 v232, v229, v229, v232 op_sel_hi:[1,1,0]
	v_fma_mix_f32 v109, v213, 1.0, v109 op_sel:[1,0,0] op_sel_hi:[1,0,0]
	v_fma_mix_f32 v232, v229, v229, v232 op_sel:[1,1,0] op_sel_hi:[1,1,0]
	v_fma_mix_f32 v110, v214, 1.0, v110 op_sel_hi:[1,0,0]
	v_fma_mix_f32 v232, v230, v230, v232 op_sel_hi:[1,1,0]
	v_fma_mix_f32 v111, v214, 1.0, v111 op_sel:[1,0,0] op_sel_hi:[1,0,0]
	v_fma_mix_f32 v232, v230, v230, v232 op_sel:[1,1,0] op_sel_hi:[1,1,0]
	v_fma_mix_f32 v112, v215, 1.0, v112 op_sel_hi:[1,0,0]
	v_fma_mix_f32 v232, v231, v231, v232 op_sel_hi:[1,1,0]
	v_fma_mix_f32 v113, v215, 1.0, v113 op_sel:[1,0,0] op_sel_hi:[1,0,0]
	v_fma_mix_f32 v232, v231, v231, v232 op_sel:[1,1,0] op_sel_hi:[1,1,0]
	v_cvt_pk_f16_f32 v114, v106, v107
	v_cvt_pk_f16_f32 v115, v108, v109
	v_add_f32_dpp v232, v232, v232 quad_perm:[1,0,3,2] row_mask:0xf bank_mask:0xf
	v_cvt_pk_f16_f32 v116, v110, v111
	v_cvt_pk_f16_f32 v117, v112, v113
	v_add_f32_dpp v232, v232, v232 quad_perm:[2,3,0,1] row_mask:0xf bank_mask:0xf
	global_store_dwordx4 v[246:247], v[114:117], off offset:256
	v_add_u32_e32 v223, 0x2800, v222
	v_add_f32_dpp v3, v232, v232 row_half_mirror row_mask:0xf bank_mask:0xf
	s_and_saveexec_b64 s[0:1], s[100:101]
	global_store_dword v223, v3, s[2:3]
	s_or_b64 exec, exec, s[0:1]
	s_waitcnt vmcnt(15)
	s_waitcnt lgkmcnt(0)
	v_fma_mix_f32 v68, v216, 1.0, v68 op_sel_hi:[1,0,0]
	v_fma_mix_f32 v118, v114, v114, 0 op_sel:[1,1,0] op_sel_hi:[1,1,0]
	v_fma_mix_f32 v69, v216, 1.0, v69 op_sel:[1,0,0] op_sel_hi:[1,0,0]
	v_fma_mix_f32 v118, v114, v114, v118 op_sel_hi:[1,1,0]
	v_fma_mix_f32 v70, v217, 1.0, v70 op_sel_hi:[1,0,0]
	v_fma_mix_f32 v118, v115, v115, v118 op_sel_hi:[1,1,0]
	v_fma_mix_f32 v71, v217, 1.0, v71 op_sel:[1,0,0] op_sel_hi:[1,0,0]
	v_fma_mix_f32 v118, v115, v115, v118 op_sel:[1,1,0] op_sel_hi:[1,1,0]
	v_fma_mix_f32 v72, v218, 1.0, v72 op_sel_hi:[1,0,0]
	v_fma_mix_f32 v118, v116, v116, v118 op_sel_hi:[1,1,0]
	v_fma_mix_f32 v73, v218, 1.0, v73 op_sel:[1,0,0] op_sel_hi:[1,0,0]
	v_fma_mix_f32 v118, v116, v116, v118 op_sel:[1,1,0] op_sel_hi:[1,1,0]
	v_fma_mix_f32 v74, v219, 1.0, v74 op_sel_hi:[1,0,0]
	v_fma_mix_f32 v118, v117, v117, v118 op_sel_hi:[1,1,0]
	v_fma_mix_f32 v75, v219, 1.0, v75 op_sel:[1,0,0] op_sel_hi:[1,0,0]
	v_fma_mix_f32 v118, v117, v117, v118 op_sel:[1,1,0] op_sel_hi:[1,1,0]
	v_cvt_pk_f16_f32 v228, v68, v69
	v_cvt_pk_f16_f32 v229, v70, v71
	v_add_f32_dpp v118, v118, v118 quad_perm:[1,0,3,2] row_mask:0xf bank_mask:0xf
	v_cvt_pk_f16_f32 v230, v72, v73
	v_cvt_pk_f16_f32 v231, v74, v75
	v_add_f32_dpp v118, v118, v118 quad_perm:[2,3,0,1] row_mask:0xf bank_mask:0xf
	global_store_dwordx4 v[248:249], v[228:231], off offset:256
	v_add_u32_e32 v223, 0x3000, v222
	v_add_f32_dpp v3, v118, v118 row_half_mirror row_mask:0xf bank_mask:0xf
	s_and_saveexec_b64 s[0:1], s[100:101]
	global_store_dword v223, v3, s[2:3]
	s_or_b64 exec, exec, s[0:1]
	v_fma_mix_f32 v232, v228, v228, 0 op_sel:[1,1,0] op_sel_hi:[1,1,0]
	s_nop 0
	v_fma_mix_f32 v232, v228, v228, v232 op_sel_hi:[1,1,0]
	s_nop 0
	v_fma_mix_f32 v232, v229, v229, v232 op_sel_hi:[1,1,0]
	s_nop 0
	v_fma_mix_f32 v232, v229, v229, v232 op_sel:[1,1,0] op_sel_hi:[1,1,0]
	s_nop 0
	v_fma_mix_f32 v232, v230, v230, v232 op_sel_hi:[1,1,0]
	s_nop 0
	v_fma_mix_f32 v232, v230, v230, v232 op_sel:[1,1,0] op_sel_hi:[1,1,0]
	s_nop 0
	v_fma_mix_f32 v232, v231, v231, v232 op_sel_hi:[1,1,0]
	s_nop 0
	v_fma_mix_f32 v232, v231, v231, v232 op_sel:[1,1,0] op_sel_hi:[1,1,0]
	s_nop 1
	v_add_f32_dpp v232, v232, v232 quad_perm:[1,0,3,2] row_mask:0xf bank_mask:0xf
	s_nop 1
	v_add_f32_dpp v232, v232, v232 quad_perm:[2,3,0,1] row_mask:0xf bank_mask:0xf
	v_add_u32_e32 v223, 0x3800, v222
	s_nop 0
	v_add_f32_dpp v3, v232, v232 row_half_mirror row_mask:0xf bank_mask:0xf
	s_and_saveexec_b64 s[0:1], s[100:101]
	global_store_dword v223, v3, s[2:3]
	s_or_b64 exec, exec, s[0:1]
	s_branch .LBB0_904
